# k7 + L0 differential-attention tile block rewritten (2-chain max, deeper fragment prefetch, no negm copy)
# speedup vs baseline: 1.0167x; 1.0034x over previous
; template <int DQK, int DV, int MODE, int QPRE, bool DIFF> ...
;     ...
;             if (!QKFIRST) {
;                 const LAS unsigned char* kb = lds + bi * BUF + l32 * KST + hi * 16;
;             {
;                 const bf16x8 a0 = *(const LAS bf16x8*)(kb), a1 = *(const LAS bf16x8*)(kb + 32 * KST);
;                 if (MODE == 1) { const f32x16 z16 = {0.f, 0.f, 0.f, 0.f, 0.f, 0.f, 0.f, 0.f, 0.f, 0.f, 0.f, 0.f, 0.f, 0.f, 0.f, 0.f};
;                     s0 = __builtin_amdgcn_mfma_f32_32x32x16_bf16(a0, qf[0], z16, 0, 0, 0); s1 = __builtin_amdgcn_mfma_f32_32x32x16_bf16(a1, qf[0], z16, 0, 0, 0); }
;                 else { s0 = __builtin_amdgcn_mfma_f32_32x32x16_bf16(a0, qf[0], negm, 0, 0, 0); s1 = __builtin_amdgcn_mfma_f32_32x32x16_bf16(a1, qf[0], negm, 0, 0, 0); }
;             }
; #pragma unroll
;             for (int d0 = 1; d0 < ND0; ++d0) {
;                 const bf16x8 a0 = *(const LAS bf16x8*)(kb + d0 * 32), a1 = *(const LAS bf16x8*)(kb + 32 * KST + d0 * 32);
;                 s0 = __builtin_amdgcn_mfma_f32_32x32x16_bf16(a0, qf[d0], s0, 0, 0, 0);
;                 s1 = __builtin_amdgcn_mfma_f32_32x32x16_bf16(a1, qf[d0], s1, 0, 0, 0);
;             }
;             }
;             bf16x8 vf[2][4];
;     ...
;             ATT_LOADV(vf[0], 0); if (!DEEP) ATT_LOADV(vf[1], 1);
;             __builtin_amdgcn_sched_barrier(0);
;             if (MODE != 1) {
;                 float mx = fmaxf(s0[0], s1[0]);
; #pragma unroll
;                 for (int r = 1; r < 16; ++r) mx = fmaxf(fmaxf(mx, s0[r]), s1[r]);
;                 { float a, b; swap32(mx, a, b); mx = fmaxf(a, b); }
;                 const bool first = (i == 0);
;                 if (first || __any(mx > 8.0f)) {
;                     const float dl = first ? mx : fmaxf(mx, 0.f);
;                     mhat += dl;
; #pragma unroll
;                     for (int r = 0; r < 16; ++r) { s0[r] -= dl; s1[r] -= dl; negm[r] = -mhat; }
;                     if (DEEP && QKFIRST && hf == 0 && (ATT_TILE(i0 + UNR - 1) <= my_last)) {
; #pragma unroll
;                         for (int r = 0; r < 16; ++r) { sq[UNR - 1][0][r] -= dl; sq[UNR - 1][1][r] -= dl; }
;                     }
;                     if (!first) {
;                         const float alpha = __builtin_amdgcn_exp2f(-dl);
;                         l_run *= alpha;
; #pragma unroll
;                         for (int i2 = 0; i2 < NDB; ++i2)
; #pragma unroll
.LBB0_575:
	s_mul_i32 s7, s5, 0x6c00
	v_add_u32_e32 v221, s7, v219
	ds_read_b128 v[148:151], v221
	ds_read_b128 v[152:155], v221 offset:4608
	ds_read_b128 v[156:159], v221 offset:32
	ds_read_b128 v[160:163], v221 offset:4640
	ds_read_b128 v[164:167], v221 offset:64
	ds_read_b128 v[168:171], v221 offset:4672
	ds_read_b128 v[172:175], v221 offset:96
	ds_read_b128 v[176:179], v221 offset:4704
	s_waitcnt lgkmcnt(7)
	v_mfma_f32_32x32x16_bf16 v[80:95], v[148:151], v[120:123], v[64:79]
	ds_read_b128 v[240:243], v221 offset:9216
	s_waitcnt lgkmcnt(7)
	v_mfma_f32_32x32x16_bf16 v[96:111], v[152:155], v[120:123], v[64:79]
	ds_read_b128 v[244:247], v221 offset:13824
	s_waitcnt lgkmcnt(7)
	v_mfma_f32_32x32x16_bf16 v[80:95], v[156:159], v[124:127], v[80:95]
	ds_read_b128 v[248:251], v221 offset:18432
	s_waitcnt lgkmcnt(7)
	v_mfma_f32_32x32x16_bf16 v[96:111], v[160:163], v[124:127], v[96:111]
	ds_read_b128 v[148:151], v221 offset:23040
	s_waitcnt lgkmcnt(7)
	v_mfma_f32_32x32x16_bf16 v[80:95], v[164:167], v[128:131], v[80:95]
	ds_read_b128 v[152:155], v221 offset:9248
	s_waitcnt lgkmcnt(7)
	v_mfma_f32_32x32x16_bf16 v[96:111], v[168:171], v[128:131], v[96:111]
	ds_read_b128 v[156:159], v221 offset:13856
	s_waitcnt lgkmcnt(7)
	v_mfma_f32_32x32x16_bf16 v[80:95], v[172:175], v[132:135], v[80:95]
	ds_read_b128 v[160:163], v221 offset:18464
	s_waitcnt lgkmcnt(7)
	v_mfma_f32_32x32x16_bf16 v[96:111], v[176:179], v[132:135], v[96:111]
	ds_read_b128 v[164:167], v221 offset:23072
	s_nop 7
	v_max3_f32 v222, v80, v81, v82
	s_nop 1
	v_max3_f32 v223, v96, v97, v98
	v_max3_f32 v222, v222, v83, v84
	v_max3_f32 v223, v223, v99, v100
	v_max3_f32 v222, v222, v85, v86
	v_max3_f32 v223, v223, v101, v102
	v_max3_f32 v222, v222, v87, v88
	v_max3_f32 v223, v223, v103, v104
	v_max3_f32 v222, v222, v89, v90
	v_max3_f32 v223, v223, v105, v106
	v_max3_f32 v222, v222, v91, v92
	v_max3_f32 v223, v223, v107, v108
	v_max3_f32 v222, v222, v93, v94
	v_max3_f32 v223, v223, v109, v110
	v_max3_f32 v222, v222, v95, v111
	v_max_f32_e32 v222, v222, v223
	v_mov_b32_e32 v223, v222
	s_nop 1
	v_permlane32_swap_b32_e32 v222, v223
	v_max_f32_e32 v222, v222, v223
	v_cmp_lt_f32_e32 vcc, s26, v222
	s_cbranch_vccnz .Ldf_rare0
.Ldf_back0:
	v_exp_f32_e32 v80, v80
	v_exp_f32_e32 v81, v81
	v_exp_f32_e32 v82, v82
	v_add_f32_e32 v223, v80, v81
	v_exp_f32_e32 v83, v83
	v_add_f32_e32 v223, v223, v82
	v_exp_f32_e32 v84, v84
	v_add_f32_e32 v223, v223, v83
	v_exp_f32_e32 v85, v85
	v_add_f32_e32 v223, v223, v84
	v_exp_f32_e32 v86, v86
	v_add_f32_e32 v223, v223, v85
	v_exp_f32_e32 v87, v87
	v_add_f32_e32 v223, v223, v86
	v_add_f32_e32 v223, v223, v87
	v_cvt_pk_bf16_f32 v80, v80, v81
	v_cvt_pk_bf16_f32 v81, v82, v83
	v_cvt_pk_bf16_f32 v82, v84, v85
	v_cvt_pk_bf16_f32 v83, v86, v87
	v_exp_f32_e32 v88, v88
	v_exp_f32_e32 v89, v89
	v_exp_f32_e32 v90, v90
	v_add_f32_e32 v223, v223, v88
	v_exp_f32_e32 v91, v91
	v_add_f32_e32 v223, v223, v89
	v_exp_f32_e32 v92, v92
	v_add_f32_e32 v223, v223, v90
	v_exp_f32_e32 v93, v93
	v_add_f32_e32 v223, v223, v91
	v_exp_f32_e32 v94, v94
	v_add_f32_e32 v223, v223, v92
	v_exp_f32_e32 v95, v95
	v_add_f32_e32 v223, v223, v93
	v_add_f32_e32 v223, v223, v94
	v_add_f32_e32 v223, v223, v95
	v_cvt_pk_bf16_f32 v84, v88, v89
	v_cvt_pk_bf16_f32 v85, v90, v91
	v_cvt_pk_bf16_f32 v86, v92, v93
	v_cvt_pk_bf16_f32 v87, v94, v95
	v_exp_f32_e32 v96, v96
	v_exp_f32_e32 v97, v97
	v_exp_f32_e32 v98, v98
	v_add_f32_e32 v224, v96, v97
	v_exp_f32_e32 v99, v99
	v_add_f32_e32 v224, v224, v98
	v_exp_f32_e32 v100, v100
	v_add_f32_e32 v224, v224, v99
	v_exp_f32_e32 v101, v101
	v_add_f32_e32 v224, v224, v100
	v_exp_f32_e32 v102, v102
	v_add_f32_e32 v224, v224, v101
	v_exp_f32_e32 v103, v103
	v_add_f32_e32 v224, v224, v102
	v_add_f32_e32 v224, v224, v103
	v_cvt_pk_bf16_f32 v88, v96, v97
	v_cvt_pk_bf16_f32 v89, v98, v99
	v_cvt_pk_bf16_f32 v90, v100, v101
	v_cvt_pk_bf16_f32 v91, v102, v103
	v_exp_f32_e32 v104, v104
	v_exp_f32_e32 v105, v105
	v_exp_f32_e32 v106, v106
	v_add_f32_e32 v224, v224, v104
	v_exp_f32_e32 v107, v107
	v_add_f32_e32 v224, v224, v105
	v_exp_f32_e32 v108, v108
	v_add_f32_e32 v224, v224, v106
	v_exp_f32_e32 v109, v109
	v_add_f32_e32 v224, v224, v107
	v_exp_f32_e32 v110, v110
	v_add_f32_e32 v224, v224, v108
	v_exp_f32_e32 v111, v111
	v_add_f32_e32 v224, v224, v109
	v_add_f32_e32 v224, v224, v110
	v_add_f32_e32 v224, v224, v111
	v_cvt_pk_bf16_f32 v92, v104, v105
	v_cvt_pk_bf16_f32 v93, v106, v107
	v_cvt_pk_bf16_f32 v94, v108, v109
	v_cvt_pk_bf16_f32 v95, v110, v111
	v_add_f32_e32 v223, v223, v224
	v_add_f32_e32 v203, v203, v223
	s_waitcnt lgkmcnt(7)
	v_mfma_f32_32x32x16_bf16 v[48:63], v[240:243], v[80:83], v[48:63]
	ds_read_b128 v[168:171], v221 offset:9280
	s_waitcnt lgkmcnt(7)
	v_mfma_f32_32x32x16_bf16 v[32:47], v[244:247], v[80:83], v[32:47]
	ds_read_b128 v[172:175], v221 offset:13888
	s_waitcnt lgkmcnt(7)
	v_mfma_f32_32x32x16_bf16 v[0:15], v[248:251], v[80:83], v[0:15]
	ds_read_b128 v[176:179], v221 offset:18496
	s_waitcnt lgkmcnt(7)
	v_mfma_f32_32x32x16_bf16 v[16:31], v[148:151], v[80:83], v[16:31]
	ds_read_b128 v[240:243], v221 offset:23104
	s_waitcnt lgkmcnt(7)
	v_mfma_f32_32x32x16_bf16 v[48:63], v[152:155], v[84:87], v[48:63]
	ds_read_b128 v[244:247], v221 offset:9312
	s_waitcnt lgkmcnt(7)
	v_mfma_f32_32x32x16_bf16 v[32:47], v[156:159], v[84:87], v[32:47]
	ds_read_b128 v[248:251], v221 offset:13920
	s_waitcnt lgkmcnt(7)
	v_mfma_f32_32x32x16_bf16 v[0:15], v[160:163], v[84:87], v[0:15]
	ds_read_b128 v[148:151], v221 offset:18528
	s_waitcnt lgkmcnt(7)
	v_mfma_f32_32x32x16_bf16 v[16:31], v[164:167], v[84:87], v[16:31]
	ds_read_b128 v[152:155], v221 offset:23136
	s_waitcnt lgkmcnt(7)
	v_mfma_f32_32x32x16_bf16 v[48:63], v[168:171], v[88:91], v[48:63]
	s_waitcnt lgkmcnt(6)
	v_mfma_f32_32x32x16_bf16 v[32:47], v[172:175], v[88:91], v[32:47]
	s_waitcnt lgkmcnt(5)
	v_mfma_f32_32x32x16_bf16 v[0:15], v[176:179], v[88:91], v[0:15]
	s_waitcnt lgkmcnt(4)
	v_mfma_f32_32x32x16_bf16 v[16:31], v[240:243], v[88:91], v[16:31]
	s_waitcnt lgkmcnt(3)
	v_mfma_f32_32x32x16_bf16 v[48:63], v[244:247], v[92:95], v[48:63]
	s_waitcnt lgkmcnt(2)
	v_mfma_f32_32x32x16_bf16 v[32:47], v[248:251], v[92:95], v[32:47]
	s_waitcnt lgkmcnt(1)
	v_mfma_f32_32x32x16_bf16 v[0:15], v[148:151], v[92:95], v[0:15]
	s_waitcnt lgkmcnt(0)
	v_mfma_f32_32x32x16_bf16 v[16:31], v[152:155], v[92:95], v[16:31]
	s_cmp_ge_u32 s6, s31
	s_cbranch_scc1 .LBB0_570

; template <int DQK, int DV, int MODE, int QPRE, bool DIFF> ...
;     ...
;                 if (first || __any(mx > 8.0f)) {
;                     const float dl = first ? mx : fmaxf(mx, 0.f);
;                     mhat += dl;
; #pragma unroll
;                     for (int r = 0; r < 16; ++r) { s0[r] -= dl; s1[r] -= dl; negm[r] = -mhat; }
;                     if (DEEP && QKFIRST && hf == 0 && (ATT_TILE(i0 + UNR - 1) <= my_last)) {
; #pragma unroll
;                         for (int r = 0; r < 16; ++r) { sq[UNR - 1][0][r] -= dl; sq[UNR - 1][1][r] -= dl; }
;                     }
;                     if (!first) {
;                         const float alpha = __builtin_amdgcn_exp2f(-dl);
;                         l_run *= alpha;
; #pragma unroll
;                         for (int i2 = 0; i2 < NDB; ++i2)
; #pragma unroll
;                             for (int r = 0; r < 16; ++r) o[i2][r] *= alpha;
;                     }
.Ldf_rare0:
	v_max_f32_e32 v238, 0, v222
	v_exp_f32_e64 v236, -v238
	v_add_f32_e32 v202, v202, v238
	s_nop 11
	v_pk_mul_f32 v[0:1], v[0:1], v[236:237] op_sel_hi:[1,0]
	v_pk_mul_f32 v[2:3], v[2:3], v[236:237] op_sel_hi:[1,0]
	v_pk_mul_f32 v[4:5], v[4:5], v[236:237] op_sel_hi:[1,0]
	v_pk_mul_f32 v[6:7], v[6:7], v[236:237] op_sel_hi:[1,0]
	v_pk_mul_f32 v[8:9], v[8:9], v[236:237] op_sel_hi:[1,0]
	v_pk_mul_f32 v[10:11], v[10:11], v[236:237] op_sel_hi:[1,0]
	v_pk_mul_f32 v[12:13], v[12:13], v[236:237] op_sel_hi:[1,0]
	v_pk_mul_f32 v[14:15], v[14:15], v[236:237] op_sel_hi:[1,0]
	v_pk_mul_f32 v[16:17], v[16:17], v[236:237] op_sel_hi:[1,0]
	v_pk_mul_f32 v[18:19], v[18:19], v[236:237] op_sel_hi:[1,0]
	v_pk_mul_f32 v[20:21], v[20:21], v[236:237] op_sel_hi:[1,0]
	v_pk_mul_f32 v[22:23], v[22:23], v[236:237] op_sel_hi:[1,0]
	v_pk_mul_f32 v[24:25], v[24:25], v[236:237] op_sel_hi:[1,0]
	v_pk_mul_f32 v[26:27], v[26:27], v[236:237] op_sel_hi:[1,0]
	v_pk_mul_f32 v[28:29], v[28:29], v[236:237] op_sel_hi:[1,0]
	v_pk_mul_f32 v[30:31], v[30:31], v[236:237] op_sel_hi:[1,0]
	v_pk_mul_f32 v[32:33], v[32:33], v[236:237] op_sel_hi:[1,0]
	v_pk_mul_f32 v[34:35], v[34:35], v[236:237] op_sel_hi:[1,0]
	v_pk_mul_f32 v[36:37], v[36:37], v[236:237] op_sel_hi:[1,0]
	v_pk_mul_f32 v[38:39], v[38:39], v[236:237] op_sel_hi:[1,0]
	v_pk_mul_f32 v[40:41], v[40:41], v[236:237] op_sel_hi:[1,0]
	v_pk_mul_f32 v[42:43], v[42:43], v[236:237] op_sel_hi:[1,0]
	v_pk_mul_f32 v[44:45], v[44:45], v[236:237] op_sel_hi:[1,0]
	v_pk_mul_f32 v[46:47], v[46:47], v[236:237] op_sel_hi:[1,0]
	v_pk_mul_f32 v[48:49], v[48:49], v[236:237] op_sel_hi:[1,0]
	v_pk_mul_f32 v[50:51], v[50:51], v[236:237] op_sel_hi:[1,0]
	v_pk_mul_f32 v[52:53], v[52:53], v[236:237] op_sel_hi:[1,0]
	v_pk_mul_f32 v[54:55], v[54:55], v[236:237] op_sel_hi:[1,0]
	v_pk_mul_f32 v[56:57], v[56:57], v[236:237] op_sel_hi:[1,0]
	v_pk_mul_f32 v[58:59], v[58:59], v[236:237] op_sel_hi:[1,0]
	v_pk_mul_f32 v[60:61], v[60:61], v[236:237] op_sel_hi:[1,0]
	v_pk_mul_f32 v[62:63], v[62:63], v[236:237] op_sel_hi:[1,0]
	v_mul_f32_e32 v203, v203, v236
	v_xor_b32_e32 v64, 0x80000000, v202
	v_mov_b32_e32 v65, v64
	v_mov_b32_e32 v66, v64
	v_mov_b32_e32 v67, v64
	v_mov_b32_e32 v68, v64
	v_mov_b32_e32 v69, v64
	v_mov_b32_e32 v70, v64
	v_mov_b32_e32 v71, v64
	v_mov_b32_e32 v72, v64
	v_mov_b32_e32 v73, v64
	v_mov_b32_e32 v74, v64
	v_mov_b32_e32 v75, v64
	v_mov_b32_e32 v76, v64
	v_mov_b32_e32 v77, v64
	v_mov_b32_e32 v78, v64
	v_mov_b32_e32 v79, v64
	v_pk_add_f32 v[80:81], v[80:81], v[238:239] op_sel_hi:[1,0] neg_lo:[0,1] neg_hi:[0,1]
	v_pk_add_f32 v[82:83], v[82:83], v[238:239] op_sel_hi:[1,0] neg_lo:[0,1] neg_hi:[0,1]
	v_pk_add_f32 v[84:85], v[84:85], v[238:239] op_sel_hi:[1,0] neg_lo:[0,1] neg_hi:[0,1]
	v_pk_add_f32 v[86:87], v[86:87], v[238:239] op_sel_hi:[1,0] neg_lo:[0,1] neg_hi:[0,1]
	v_pk_add_f32 v[88:89], v[88:89], v[238:239] op_sel_hi:[1,0] neg_lo:[0,1] neg_hi:[0,1]
	v_pk_add_f32 v[90:91], v[90:91], v[238:239] op_sel_hi:[1,0] neg_lo:[0,1] neg_hi:[0,1]
	v_pk_add_f32 v[92:93], v[92:93], v[238:239] op_sel_hi:[1,0] neg_lo:[0,1] neg_hi:[0,1]
	v_pk_add_f32 v[94:95], v[94:95], v[238:239] op_sel_hi:[1,0] neg_lo:[0,1] neg_hi:[0,1]
	v_pk_add_f32 v[96:97], v[96:97], v[238:239] op_sel_hi:[1,0] neg_lo:[0,1] neg_hi:[0,1]
	v_pk_add_f32 v[98:99], v[98:99], v[238:239] op_sel_hi:[1,0] neg_lo:[0,1] neg_hi:[0,1]
	v_pk_add_f32 v[100:101], v[100:101], v[238:239] op_sel_hi:[1,0] neg_lo:[0,1] neg_hi:[0,1]
	v_pk_add_f32 v[102:103], v[102:103], v[238:239] op_sel_hi:[1,0] neg_lo:[0,1] neg_hi:[0,1]
	v_pk_add_f32 v[104:105], v[104:105], v[238:239] op_sel_hi:[1,0] neg_lo:[0,1] neg_hi:[0,1]
	v_pk_add_f32 v[106:107], v[106:107], v[238:239] op_sel_hi:[1,0] neg_lo:[0,1] neg_hi:[0,1]
	v_pk_add_f32 v[108:109], v[108:109], v[238:239] op_sel_hi:[1,0] neg_lo:[0,1] neg_hi:[0,1]
	v_pk_add_f32 v[110:111], v[110:111], v[238:239] op_sel_hi:[1,0] neg_lo:[0,1] neg_hi:[0,1]
	s_nop 1
	s_branch .Ldf_back0
